# attention queue order: chunk-band blk1 group moved to position 9 (right after the first 32 entries plus one group)
# baseline (speedup 1.0000x reference)
.LBB0_261:
	s_lshl_b32 s0, s52, 3
	s_add_i32 s0, s0, 0
	s_add_i32 s0, s0, 0x19440
	v_mov_b32_e32 v0, s0
	s_waitcnt lgkmcnt(0)
	s_barrier
	ds_read_b64 v[2:3], v0
	s_waitcnt lgkmcnt(0)
	v_readfirstlane_b32 s8, v2
	s_cmp_lt_i32 s8, 0
	v_readfirstlane_b32 s20, v3
	s_cbranch_scc1 .LBB0_309
	s_lshr_b32 s12, s8, 2
	s_lshl_b32 s12, s12, 2
	s_mov_b32 s14, 0x87543210
	s_mov_b32 s15, 0xfedcba69
	s_lshr_b64 s[14:15], s[14:15], s12
	s_and_b32 s14, s14, 15
	s_and_b32 s13, s8, 3
	s_lshl_b32 s14, s14, 2
	s_or_b32 s8, s14, s13
	s_lshr_b32 s9, s8, 2
	s_cmp_gt_u32 s8, 23
	s_mov_b64 s[2:3], -1
	s_cbranch_scc0 .LBB0_268
	s_mov_b64 s[2:3], 0
	s_mov_b32 s98, 1
	s_cmp_eq_u32 s9, 6
	s_mov_b64 s[0:1], 0
	s_cbranch_scc1 .LBB0_268
	s_cmp_gt_u32 s8, 55
	s_mov_b64 s[6:7], -1
	s_cbranch_scc0 .LBB0_266
	s_cmp_lg_u32 s9, 14
	s_mov_b64 s[6:7], 0
	s_cselect_b64 s[0:1], -1, 0
